# barrier-slack placement: layer-1 w_gate conversion rounds moved from the merge->out / out->gate-up barriers to the gate-up->down / down->next barriers
# baseline (speedup 1.0000x reference)
; __device__ __forceinline__ unsigned cvt_pk_bf16(float lo, float hi) { unsigned r; asm volatile("v_cvt_pk_bf16_f32 %0, %1, %2" : "=v"(r) : "v"(lo), "v"(hi)); return r; }
; __device__ __forceinline__ void st16_wt(void* p, u32x4 v) { asm volatile("global_store_dwordx4 %0, %1, off sc1\n\ts_nop 1" :: "v"(p), "v"(v) : "memory"); }
; #define SEAM(k) do { if (IN(k) && IN((k) + 1)) { if (hi > 4096) cg::this_grid().sync(); else xcd_barrier(bar); } } while (0)
; __device__ __forceinline__ void tr_item(const float* __restrict__ W, int K, int N, bf16_t* WT, const float* __restrict__ kscale, int rowmode, int item, int lane) {
;     const int nblk = N >> 5, kb = item / nblk, nb = item - kb * nblk;
;     const int c = lane >> 3, q = lane & 7, k0 = kb * 64 + c * 8, n0 = nb * 32 + q * 4;
;     f32x4 v[8];
; #pragma unroll
;     for (int i = 0; i < 8; ++i) v[i] = __builtin_nontemporal_load((const f32x4*)(W + (size_t)(k0 + i) * N + n0));
;     if (kscale) { const f32x4 s0 = *(const f32x4*)(kscale + k0), s1 = *(const f32x4*)(kscale + k0 + 4);
; #pragma unroll
;         for (int i = 0; i < 4; ++i) { v[i] = v[i] * s0[i]; v[4 + i] = v[4 + i] * s1[i]; } }
;     int drow;
;     if (rowmode == 0) drow = n0;
;     else if (rowmode == 3) { const int g = n0 - pg8::C_GA; drow = g < 0 ? n0 : pg8::C_GA + (((g & 2047) >> 7) << 8) + ((g >> 11) << 7) + (g & 127); }
;     else drow = ((n0 >> 7) << 8) + (n0 & 127) + (rowmode == 2 ? 128 : 0);
; #pragma unroll
;     for (int e = 0; e < 4; ++e) { u32x4 o; o.x = cvt_pk_bf16(v[0][e], v[1][e]); o.y = cvt_pk_bf16(v[2][e], v[3][e]); o.z = cvt_pk_bf16(v[4][e], v[5][e]); o.w = cvt_pk_bf16(v[6][e], v[7][e]);
;         pg8::st16_wt(WT + (size_t)(drow + e) * K + k0, o); }
; __global__ void __launch_bounds__(NTHREADS, 2) mk_fwd(Args args) {
;     ...
;         SEAM(pb + 4);
.LBB0_769:
	s_or_b64 exec, exec, s[18:19]
	s_waitcnt vmcnt(0)
.LBB0_770:
	s_or_b64 exec, exec, s[0:1]
	s_cmpk_lg_u32 s3, 0x100
	s_cbranch_scc1 .Lcv_skip_3
	v_readfirstlane_b32 vcc_lo, v204
	s_nop 3
	s_lshr_b32 vcc_lo, vcc_lo, 6
	s_cmp_eq_u32 vcc_lo, 0
	s_cbranch_scc1 .Lcv_skip_3
	s_cmp_lg_u32 s64, 0
	s_cbranch_scc1 .Lcv_pfwait_3
	v_and_b32_e32 v106, 63, v204
	v_lshrrev_b32_e32 v107, 3, v106
	v_and_b32_e32 v108, 7, v106
	v_readfirstlane_b32 vcc_lo, v204
	s_nop 3
	s_lshr_b32 vcc_lo, vcc_lo, 6
	s_mul_i32 vcc_hi, s85, 7
	s_add_i32 vcc_lo, vcc_lo, vcc_hi
	s_add_i32 vcc_lo, vcc_lo, -1
	s_add_i32 vcc_lo, vcc_lo, 3584
	s_sub_u32 vcc_lo, vcc_lo, 3520
	v_mov_b32_e32 v113, vcc_lo
	v_mul_u32_u24_e32 v109, 0x5d18, v113
	v_lshrrev_b32_e32 v109, 22, v109
	v_mul_u32_u24_e32 v110, 0xb0, v109
	v_sub_u32_e32 v110, v113, v110
	v_lshlrev_b32_e32 v109, 6, v109
	v_lshl_add_u32 v109, v107, 3, v109
	v_lshlrev_b32_e32 v110, 5, v110
	v_lshl_add_u32 v110, v108, 2, v110
	v_mul_u32_u24_e32 v111, 0x5800, v109
	v_lshl_add_u32 v111, v110, 2, v111
	v_add_u32_e32 v111, 0x2c00000, v111
	v_lshrrev_b32_e32 v112, 7, v110
	v_lshlrev_b32_e32 v112, 8, v112
	v_and_b32_e32 v113, 0x7f, v110
	v_add_u32_e32 v112, v112, v113
	v_lshlrev_b32_e32 v112, 12, v112
	v_lshl_add_u32 v112, v109, 1, v112
	v_lshlrev_b32_e32 v113, 2, v109
	v_add_u32_e32 v113, 0x2000, v113
	v_readlane_b32 vcc_lo, v250, 28
	v_readlane_b32 vcc_hi, v250, 29
	s_nop 4
	global_load_dwordx4 v[98:101], v113, vcc
	global_load_dwordx4 v[102:105], v113, vcc offset:16
	v_readlane_b32 vcc_lo, v250, 30
	v_readlane_b32 vcc_hi, v250, 31
	s_nop 4
	global_load_dwordx4 v[66:69], v111, vcc nt
	v_add_u32_e32 v111, 0x5800, v111
	global_load_dwordx4 v[70:73], v111, vcc nt
	v_add_u32_e32 v111, 0x5800, v111
	global_load_dwordx4 v[74:77], v111, vcc nt
	v_add_u32_e32 v111, 0x5800, v111
	global_load_dwordx4 v[78:81], v111, vcc nt
	v_add_u32_e32 v111, 0x5800, v111
	global_load_dwordx4 v[82:85], v111, vcc nt
	v_add_u32_e32 v111, 0x5800, v111
	global_load_dwordx4 v[86:89], v111, vcc nt
	v_add_u32_e32 v111, 0x5800, v111
	global_load_dwordx4 v[90:93], v111, vcc nt
	v_add_u32_e32 v111, 0x5800, v111
	global_load_dwordx4 v[94:97], v111, vcc nt
	v_readlane_b32 vcc_lo, v250, 36
	v_readlane_b32 vcc_hi, v250, 37
	s_nop 3
	s_add_u32 vcc_lo, vcc_lo, 0x89c0000
	s_addc_u32 vcc_hi, vcc_hi, 0
	s_waitcnt vmcnt(0)
	v_mul_f32_e32 v66, v66, v98
	v_mul_f32_e32 v67, v67, v98
	v_mul_f32_e32 v68, v68, v98
	v_mul_f32_e32 v69, v69, v98
	v_mul_f32_e32 v70, v70, v99
	v_mul_f32_e32 v71, v71, v99
	v_mul_f32_e32 v72, v72, v99
	v_mul_f32_e32 v73, v73, v99
	v_mul_f32_e32 v74, v74, v100
	v_mul_f32_e32 v75, v75, v100
	v_mul_f32_e32 v76, v76, v100
	v_mul_f32_e32 v77, v77, v100
	v_mul_f32_e32 v78, v78, v101
	v_mul_f32_e32 v79, v79, v101
	v_mul_f32_e32 v80, v80, v101
	v_mul_f32_e32 v81, v81, v101
	v_mul_f32_e32 v82, v82, v102
	v_mul_f32_e32 v83, v83, v102
	v_mul_f32_e32 v84, v84, v102
	v_mul_f32_e32 v85, v85, v102
	v_mul_f32_e32 v86, v86, v103
	v_mul_f32_e32 v87, v87, v103
	v_mul_f32_e32 v88, v88, v103
	v_mul_f32_e32 v89, v89, v103
	v_mul_f32_e32 v90, v90, v104
	v_mul_f32_e32 v91, v91, v104
	v_mul_f32_e32 v92, v92, v104
	v_mul_f32_e32 v93, v93, v104
	v_mul_f32_e32 v94, v94, v105
	v_mul_f32_e32 v95, v95, v105
	v_mul_f32_e32 v96, v96, v105
	v_mul_f32_e32 v97, v97, v105
	v_cvt_pk_bf16_f32 v114, v66, v70
	v_cvt_pk_bf16_f32 v115, v74, v78
	v_cvt_pk_bf16_f32 v116, v82, v86
	v_cvt_pk_bf16_f32 v117, v90, v94
	v_cvt_pk_bf16_f32 v118, v67, v71
	v_cvt_pk_bf16_f32 v119, v75, v79
	v_cvt_pk_bf16_f32 v120, v83, v87
	v_cvt_pk_bf16_f32 v121, v91, v95
	v_cvt_pk_bf16_f32 v122, v68, v72
	v_cvt_pk_bf16_f32 v123, v76, v80
	v_cvt_pk_bf16_f32 v124, v84, v88
	v_cvt_pk_bf16_f32 v125, v92, v96
	v_cvt_pk_bf16_f32 v126, v69, v73
	v_cvt_pk_bf16_f32 v127, v77, v81
	v_cvt_pk_bf16_f32 v128, v85, v89
	v_cvt_pk_bf16_f32 v129, v93, v97
	global_store_dwordx4 v112, v[114:117], vcc sc1
	v_add_u32_e32 v112, 0x1000, v112
	global_store_dwordx4 v112, v[118:121], vcc sc1
	v_add_u32_e32 v112, 0x1000, v112
	global_store_dwordx4 v112, v[122:125], vcc sc1
	v_add_u32_e32 v112, 0x1000, v112
	global_store_dwordx4 v112, v[126:129], vcc sc1
